# scan G stage: the second s-tile's B/acs/dt fragment LDS reads are issued behind the first tile's last MFMA (new registers, counted waits), overlapping their latency with the first tile's VALU
# speedup vs baseline: 1.0067x; 1.0021x over previous
; #define LAS __attribute__((address_space(3)))
; __device__ __forceinline__ unsigned pk2(float lo, float hi) { unsigned r; asm volatile("v_cvt_pk_bf16_f32 %0, %1, %2" : "=v"(r) : "v"(lo), "v"(hi)); return r; }
; template <bool DRY>
; __device__ __forceinline__ void ssd_chunk(SsdRegs& R, f32x4 (&st)[2], LAS unsigned char* L, bf16_t* BIG, const float* DT, float* SSQY, const SsdItem& I, int c, int tid, int lane, int wave, int li, int pi, int c16, int q4) {
;     ...
;     bf16x8 cfr[4];
; #pragma unroll
;     for (int kk = 0; kk < 4; ++kk) cfr[kk] = SSD_FRAG(CS, PC, 16 * li, kk);
;     {
;         const int l = 16 * li + c16; const float acs_l = *(const LAS float*)(SCW + l * 4);
; #pragma unroll
;         for (int t = 0; t < 2; ++t) {
;             const int si = 2 * pi + t;
;             u32x2 w; w.x = 0u; w.y = 0u;
;             if (si <= li) {
;                 f32x4 d = (f32x4){0.f, 0.f, 0.f, 0.f};
; #pragma unroll
;                 for (int kk = 0; kk < 4; ++kk) d = __builtin_amdgcn_mfma_f32_16x16x32_bf16(SSD_FRAG(BS, PC, 16 * si, kk), cfr[kk], d, 0, 0, 0);
;                 float gv[4];
;                 const f32x4 acs_s = *(const LAS f32x4*)(SCW + (16 * si + 4 * q4) * 4), dt_s = *(const LAS f32x4*)(SCW + 256 + (16 * si + 4 * q4) * 4);
; #pragma unroll
;                 for (int e = 0; e < 4; ++e) gv[e] = d[e] * __expf(acs_l - acs_s[e]) * dt_s[e];
;                 if (si == li) {
; #pragma unroll
;                     for (int e = 0; e < 4; ++e) gv[e] = (4 * q4 + e <= c16) ? gv[e] : 0.f;
;                 }
;                 w.x = pk2(gv[0], gv[1]); w.y = pk2(gv[2], gv[3]);
;             }
.LBB0_727:
	ds_read_b128 v[70:73], v131
	ds_read_b128 v[66:69], v131 offset:64
	ds_read_b128 v[62:65], v131 offset:128
	ds_read_b128 v[58:61], v131 offset:192
	ds_read_b32 v76, v132
	v_mov_b32_e32 v106, 0
	s_not_b64 s[22:23], s[88:89]
	s_andn2_b64 vcc, exec, s[88:89]
	v_mov_b32_e32 v107, v106
	s_cbranch_vccnz .LBB0_729
	ds_read_b128 v[144:147], v133 offset:17408
	ds_read_b128 v[148:151], v133 offset:17472
	ds_read_b128 v[176:179], v133 offset:17536
	ds_read_b128 v[180:183], v133 offset:17600
	ds_read_b128 v[184:187], v134
	ds_read_b128 v[152:155], v134 offset:256
	s_waitcnt lgkmcnt(5)
	v_mfma_f32_16x16x32_bf16 v[144:147], v[144:147], v[70:73], 0
	s_waitcnt lgkmcnt(4)
	v_mfma_f32_16x16x32_bf16 v[144:147], v[148:151], v[66:69], v[144:147]
	s_waitcnt lgkmcnt(3)
	v_mfma_f32_16x16x32_bf16 v[144:147], v[176:179], v[62:65], v[144:147]
	s_waitcnt lgkmcnt(2)
	v_mfma_f32_16x16x32_bf16 v[144:147], v[180:183], v[58:61], v[144:147]
	ds_read_b128 v[220:223], v135 offset:17408
	ds_read_b128 v[224:227], v135 offset:17472
	ds_read_b128 v[228:231], v135 offset:17536
	ds_read_b128 v[232:235], v135 offset:17600
	ds_read_b128 v[236:239], v136
	ds_read_b128 v[188:191], v136 offset:256
	s_waitcnt lgkmcnt(7)
	v_sub_f32_e32 v106, v76, v184
	v_sub_f32_e32 v107, v76, v185
	v_exp_f32_e32 v106, v106
	v_exp_f32_e32 v107, v107
	v_sub_f32_e32 v143, v76, v186
	v_pk_mul_f32 v[106:107], v[144:145], v[106:107]
	v_exp_f32_e32 v144, v143
	v_sub_f32_e32 v143, v76, v187
	v_exp_f32_e32 v145, v143
	s_waitcnt lgkmcnt(6)
	v_pk_mul_f32 v[106:107], v[152:153], v[106:107]
	v_pk_mul_f32 v[144:145], v[146:147], v[144:145]
	s_nop 0
	v_pk_mul_f32 v[144:145], v[154:155], v[144:145]
	v_cndmask_b32_e64 v143, v106, 0, s[6:7]
	v_cndmask_b32_e64 v146, 0, v107, s[8:9]
	v_cndmask_b32_e64 v147, v144, 0, s[10:11]
	v_cndmask_b32_e64 v148, v145, 0, s[12:13]
	v_cndmask_b32_e64 v106, v106, v143, s[4:5]
	v_cndmask_b32_e64 v107, v107, v146, s[4:5]
	v_cndmask_b32_e64 v144, v144, v147, s[4:5]
	v_cndmask_b32_e64 v145, v145, v148, s[4:5]
	v_cvt_pk_bf16_f32 v106, v106, v107
	v_cvt_pk_bf16_f32 v107, v144, v145

; #define LAS __attribute__((address_space(3)))
; __device__ __forceinline__ unsigned pk2(float lo, float hi) { unsigned r; asm volatile("v_cvt_pk_bf16_f32 %0, %1, %2" : "=v"(r) : "v"(lo), "v"(hi)); return r; }
; template <bool DRY>
; __device__ __forceinline__ void ssd_chunk(SsdRegs& R, f32x4 (&st)[2], LAS unsigned char* L, bf16_t* BIG, const float* DT, float* SSQY, const SsdItem& I, int c, int tid, int lane, int wave, int li, int pi, int c16, int q4) {
;     ...
; #pragma unroll
;         for (int t = 0; t < 2; ++t) {
;             const int si = 2 * pi + t;
;             u32x2 w; w.x = 0u; w.y = 0u;
;             if (si <= li) {
;                 f32x4 d = (f32x4){0.f, 0.f, 0.f, 0.f};
; #pragma unroll
;                 for (int kk = 0; kk < 4; ++kk) d = __builtin_amdgcn_mfma_f32_16x16x32_bf16(SSD_FRAG(BS, PC, 16 * si, kk), cfr[kk], d, 0, 0, 0);
;                 float gv[4];
;                 const f32x4 acs_s = *(const LAS f32x4*)(SCW + (16 * si + 4 * q4) * 4), dt_s = *(const LAS f32x4*)(SCW + 256 + (16 * si + 4 * q4) * 4);
; #pragma unroll
;                 for (int e = 0; e < 4; ++e) gv[e] = d[e] * __expf(acs_l - acs_s[e]) * dt_s[e];
;                 if (si == li) {
; #pragma unroll
;                     for (int e = 0; e < 4; ++e) gv[e] = (4 * q4 + e <= c16) ? gv[e] : 0.f;
;                 }
;                 w.x = pk2(gv[0], gv[1]); w.y = pk2(gv[2], gv[3]);
;             }
.LBB0_731:
	v_mov_b32_e32 v106, 0
	s_andn2_b64 vcc, exec, s[0:1]
	v_mov_b32_e32 v107, 0
	s_cbranch_vccnz .LBB0_733
	s_waitcnt lgkmcnt(6)
	v_mfma_f32_16x16x32_bf16 v[146:149], v[220:223], v[70:73], 0
	s_waitcnt lgkmcnt(5)
	v_mfma_f32_16x16x32_bf16 v[146:149], v[224:227], v[66:69], v[146:149]
	s_waitcnt lgkmcnt(4)
	v_mfma_f32_16x16x32_bf16 v[146:149], v[228:231], v[62:65], v[146:149]
	s_waitcnt lgkmcnt(3)
	v_mfma_f32_16x16x32_bf16 v[146:149], v[232:235], v[58:61], v[146:149]
	s_waitcnt lgkmcnt(2)
	v_sub_f32_e32 v106, v76, v236
	v_sub_f32_e32 v107, v76, v237
	v_exp_f32_e32 v106, v106
	v_exp_f32_e32 v107, v107
	v_sub_f32_e32 v143, v76, v238
	v_sub_f32_e32 v76, v76, v239
	v_pk_mul_f32 v[106:107], v[146:147], v[106:107]
	v_exp_f32_e32 v146, v143
	v_exp_f32_e32 v147, v76
	s_waitcnt lgkmcnt(1)
	v_pk_mul_f32 v[106:107], v[188:189], v[106:107]
	v_pk_mul_f32 v[146:147], v[148:149], v[146:147]
	s_nop 0
	v_pk_mul_f32 v[146:147], v[190:191], v[146:147]
	v_cndmask_b32_e64 v76, v106, 0, s[6:7]
	v_cndmask_b32_e64 v143, 0, v107, s[8:9]
	v_cndmask_b32_e64 v145, v146, 0, s[10:11]
	v_cndmask_b32_e64 v148, v147, 0, s[12:13]
	v_cndmask_b32_e64 v76, v106, v76, s[14:15]
	v_cndmask_b32_e64 v106, v107, v143, s[14:15]
	v_cndmask_b32_e64 v145, v146, v145, s[14:15]
	v_cndmask_b32_e64 v146, v147, v148, s[14:15]
	v_cvt_pk_bf16_f32 v106, v76, v106
	v_cvt_pk_bf16_f32 v107, v145, v146

; #define LAS __attribute__((address_space(3)))
; __device__ __forceinline__ unsigned pk2(float lo, float hi) { unsigned r; asm volatile("v_cvt_pk_bf16_f32 %0, %1, %2" : "=v"(r) : "v"(lo), "v"(hi)); return r; }
; template <bool DRY>
; __device__ __forceinline__ void ssd_chunk(SsdRegs& R, f32x4 (&st)[2], LAS unsigned char* L, bf16_t* BIG, const float* DT, float* SSQY, const SsdItem& I, int c, int tid, int lane, int wave, int li, int pi, int c16, int q4) {
;     ...
;     bf16x8 cfr[4];
; #pragma unroll
;     for (int kk = 0; kk < 4; ++kk) cfr[kk] = SSD_FRAG(CS, PC, 16 * li, kk);
;     {
;         const int l = 16 * li + c16; const float acs_l = *(const LAS float*)(SCW + l * 4);
; #pragma unroll
;         for (int t = 0; t < 2; ++t) {
;             const int si = 2 * pi + t;
;             u32x2 w; w.x = 0u; w.y = 0u;
;             if (si <= li) {
;                 f32x4 d = (f32x4){0.f, 0.f, 0.f, 0.f};
; #pragma unroll
;                 for (int kk = 0; kk < 4; ++kk) d = __builtin_amdgcn_mfma_f32_16x16x32_bf16(SSD_FRAG(BS, PC, 16 * si, kk), cfr[kk], d, 0, 0, 0);
;                 float gv[4];
;                 const f32x4 acs_s = *(const LAS f32x4*)(SCW + (16 * si + 4 * q4) * 4), dt_s = *(const LAS f32x4*)(SCW + 256 + (16 * si + 4 * q4) * 4);
; #pragma unroll
;                 for (int e = 0; e < 4; ++e) gv[e] = d[e] * __expf(acs_l - acs_s[e]) * dt_s[e];
;                 if (si == li) {
; #pragma unroll
;                     for (int e = 0; e < 4; ++e) gv[e] = (4 * q4 + e <= c16) ? gv[e] : 0.f;
;                 }
;                 w.x = pk2(gv[0], gv[1]); w.y = pk2(gv[2], gv[3]);
;             }
.LBB0_742:
	ds_read_b128 v[70:73], v131
	ds_read_b128 v[66:69], v131 offset:64
	ds_read_b128 v[62:65], v131 offset:128
	ds_read_b128 v[58:61], v131 offset:192
	ds_read_b32 v76, v132
	v_mov_b32_e32 v100, 0
	s_and_b64 vcc, exec, s[22:23]
	v_mov_b32_e32 v101, v100
	s_cbranch_vccnz .LBB0_748
	ds_read_b128 v[100:103], v133 offset:17408
	ds_read_b128 v[148:151], v133 offset:17472
	ds_read_b128 v[176:179], v133 offset:17536
	ds_read_b128 v[180:183], v133 offset:17600
	ds_read_b128 v[184:187], v134
	ds_read_b128 v[152:155], v134 offset:256
	s_waitcnt lgkmcnt(5)
	v_mfma_f32_16x16x32_bf16 v[100:103], v[100:103], v[70:73], 0
	s_waitcnt lgkmcnt(4)
	v_mfma_f32_16x16x32_bf16 v[100:103], v[148:151], v[66:69], v[100:103]
	s_waitcnt lgkmcnt(3)
	v_mfma_f32_16x16x32_bf16 v[100:103], v[176:179], v[62:65], v[100:103]
	s_waitcnt lgkmcnt(2)
	v_mfma_f32_16x16x32_bf16 v[100:103], v[180:183], v[58:61], v[100:103]
	ds_read_b128 v[220:223], v135 offset:17408
	ds_read_b128 v[224:227], v135 offset:17472
	ds_read_b128 v[228:231], v135 offset:17536
	ds_read_b128 v[232:235], v135 offset:17600
	ds_read_b128 v[236:239], v136
	ds_read_b128 v[188:191], v136 offset:256
	s_waitcnt lgkmcnt(7)
	v_sub_f32_e32 v104, v76, v184
	v_sub_f32_e32 v105, v76, v185
	v_exp_f32_e32 v104, v104
	v_exp_f32_e32 v105, v105
	s_nop 0
	v_pk_mul_f32 v[100:101], v[100:101], v[104:105]
	v_sub_f32_e32 v104, v76, v186
	v_sub_f32_e32 v105, v76, v187
	v_exp_f32_e32 v104, v104
	v_exp_f32_e32 v105, v105
	s_waitcnt lgkmcnt(6)
	v_pk_mul_f32 v[100:101], v[152:153], v[100:101]
	v_pk_mul_f32 v[102:103], v[102:103], v[104:105]
	s_nop 0
	v_pk_mul_f32 v[102:103], v[154:155], v[102:103]
	v_cndmask_b32_e64 v104, v100, 0, s[6:7]
	v_cndmask_b32_e64 v105, 0, v101, s[8:9]
	v_cndmask_b32_e64 v142, v102, 0, s[10:11]
	v_cndmask_b32_e64 v148, v103, 0, s[12:13]
	v_cndmask_b32_e64 v100, v100, v104, s[4:5]
	v_cndmask_b32_e64 v101, v101, v105, s[4:5]
	v_cndmask_b32_e64 v102, v102, v142, s[4:5]
	v_cndmask_b32_e64 v103, v103, v148, s[4:5]
	v_cvt_pk_bf16_f32 v100, v100, v101
	v_cvt_pk_bf16_f32 v101, v102, v103
	s_and_b64 vcc, exec, s[24:25]
	s_mov_b64 s[0:1], -1
	ds_write_b64 v144, v[100:101]
	s_cbranch_vccz .LBB0_749

; #define LAS __attribute__((address_space(3)))
; __device__ __forceinline__ unsigned pk2(float lo, float hi) { unsigned r; asm volatile("v_cvt_pk_bf16_f32 %0, %1, %2" : "=v"(r) : "v"(lo), "v"(hi)); return r; }
; template <bool DRY>
; __device__ __forceinline__ void ssd_chunk(SsdRegs& R, f32x4 (&st)[2], LAS unsigned char* L, bf16_t* BIG, const float* DT, float* SSQY, const SsdItem& I, int c, int tid, int lane, int wave, int li, int pi, int c16, int q4) {
;     ...
; #pragma unroll
;         for (int t = 0; t < 2; ++t) {
;             const int si = 2 * pi + t;
;             u32x2 w; w.x = 0u; w.y = 0u;
;             if (si <= li) {
;                 f32x4 d = (f32x4){0.f, 0.f, 0.f, 0.f};
; #pragma unroll
;                 for (int kk = 0; kk < 4; ++kk) d = __builtin_amdgcn_mfma_f32_16x16x32_bf16(SSD_FRAG(BS, PC, 16 * si, kk), cfr[kk], d, 0, 0, 0);
;                 float gv[4];
;                 const f32x4 acs_s = *(const LAS f32x4*)(SCW + (16 * si + 4 * q4) * 4), dt_s = *(const LAS f32x4*)(SCW + 256 + (16 * si + 4 * q4) * 4);
; #pragma unroll
;                 for (int e = 0; e < 4; ++e) gv[e] = d[e] * __expf(acs_l - acs_s[e]) * dt_s[e];
;                 if (si == li) {
; #pragma unroll
;                     for (int e = 0; e < 4; ++e) gv[e] = (4 * q4 + e <= c16) ? gv[e] : 0.f;
;                 }
;                 w.x = pk2(gv[0], gv[1]); w.y = pk2(gv[2], gv[3]);
;             }
.LBB0_745:
	s_waitcnt lgkmcnt(6)
	v_mfma_f32_16x16x32_bf16 v[100:103], v[220:223], v[70:73], 0
	s_waitcnt lgkmcnt(5)
	v_mfma_f32_16x16x32_bf16 v[100:103], v[224:227], v[66:69], v[100:103]
	s_waitcnt lgkmcnt(4)
	v_mfma_f32_16x16x32_bf16 v[100:103], v[228:231], v[62:65], v[100:103]
	s_waitcnt lgkmcnt(3)
	v_mfma_f32_16x16x32_bf16 v[100:103], v[232:235], v[58:61], v[100:103]
	s_nop 1
	s_waitcnt lgkmcnt(2)
	v_sub_f32_e32 v104, v76, v236
	v_sub_f32_e32 v105, v76, v237
	v_exp_f32_e32 v104, v104
	v_exp_f32_e32 v105, v105
	s_nop 0
	v_pk_mul_f32 v[100:101], v[100:101], v[104:105]
	v_sub_f32_e32 v104, v76, v238
	v_sub_f32_e32 v76, v76, v239
	v_exp_f32_e32 v104, v104
	v_exp_f32_e32 v105, v76
	s_waitcnt lgkmcnt(1)
	v_pk_mul_f32 v[100:101], v[188:189], v[100:101]
	v_pk_mul_f32 v[102:103], v[102:103], v[104:105]
	s_nop 0
	v_pk_mul_f32 v[102:103], v[190:191], v[102:103]
	v_cndmask_b32_e64 v76, v100, 0, s[6:7]
	v_cndmask_b32_e64 v104, 0, v101, s[8:9]
	v_cndmask_b32_e64 v105, v102, 0, s[10:11]
	v_cndmask_b32_e64 v142, v103, 0, s[12:13]
	v_cndmask_b32_e64 v76, v100, v76, s[14:15]
	v_cndmask_b32_e64 v100, v101, v104, s[14:15]
	v_cndmask_b32_e64 v102, v102, v105, s[14:15]
	v_cndmask_b32_e64 v103, v103, v142, s[14:15]
	v_cvt_pk_bf16_f32 v100, v76, v100
	v_cvt_pk_bf16_f32 v101, v102, v103
